# conv loop counted wait: the row load issued at the loop top is waited for at its first use one sub-iteration later instead of immediately
# baseline (speedup 1.0000x reference)
.LBB0_199:
	s_or_b64 exec, exec, s[6:7]
	v_sub_u32_e32 v56, v88, v87
	v_cmp_gt_u32_e32 vcc, -3, v56
	s_and_b64 exec, exec, vcc
	s_cbranch_execz .LBB0_242
	v_mov_b32_e32 v56, 0
	v_readlane_b32 s0, v253, 41
	v_mov_b32_e32 v91, v56
	v_readlane_b32 s1, v253, 42
	v_mov_b32_e32 v93, v56
	v_ashrrev_i32_e32 v87, 31, v86
	v_lshl_add_u64 v[58:59], s[0:1], 0, v[90:91]
	v_lshl_add_u64 v[80:81], v[58:59], 0, v[92:93]
	v_lshlrev_b64 v[58:59], 9, v[86:87]
	v_and_b32_e32 v57, 0x1f0, v100
	v_or_b32_e32 v58, v58, v57
	v_lshl_add_u64 v[58:59], v[58:59], 0, v[90:91]
	v_lshl_add_u64 v[58:59], s[66:67], 0, v[58:59]
	s_mov_b64 s[0:1], 0x13400000
	v_lshl_add_u64 v[88:89], v[58:59], 0, s[0:1]
	v_add_u32_e32 v58, 3, v86
	v_ashrrev_i32_e32 v59, 31, v58
	v_lshlrev_b64 v[58:59], 9, v[58:59]
	v_or_b32_e32 v58, v58, v57
	v_lshl_add_u64 v[58:59], v[58:59], 0, v[90:91]
	v_lshl_add_u64 v[58:59], s[66:67], 0, v[58:59]
	v_lshlrev_b32_e32 v82, 9, v86
	v_lshl_add_u64 v[90:91], v[58:59], 0, s[0:1]
	s_mov_b64 s[6:7], 0
	s_mov_b32 s10, 0xc000
	s_mov_b32 s11, 0x8000
	s_movk_i32 s12, 0x7fff
	s_movk_i32 s13, 0x7ffe
	s_movk_i32 s14, 0x7ffd
	v_mov_b32_e32 v83, 0x2000
	v_mov_b32_e32 v123, 0x1000
	s_mov_b64 s[8:9], 0
	s_waitcnt vmcnt(0)
	s_branch .LBB0_202

.LBB0_204:
	s_or_b64 exec, exec, s[0:1]
	v_cmp_gt_i32_e32 vcc, s11, v86
	s_waitcnt vmcnt(2)
	v_mov_b64_e32 v[76:77], v[38:39]
	v_mov_b32_e32 v59, v45
	v_cndmask_b32_e32 v57, v83, v123, vcc
	v_add_u32_e32 v58, -1, v57
	v_and_b32_e32 v98, v58, v86
	v_or_b32_e32 v58, 2, v57
	v_cmp_lt_u32_e32 vcc, 1, v98
	v_cmp_lt_u32_e64 s[0:1], v98, v58
	s_and_b64 s[16:17], vcc, s[0:1]
	v_mov_b32_e32 v58, v44
	v_mov_b32_e32 v92, v46
	v_mov_b32_e32 v93, v47
	v_mov_b32_e32 v94, v36
	v_mov_b32_e32 v95, v37
	v_mov_b32_e32 v96, v38
	v_mov_b32_e32 v97, v39
	s_and_saveexec_b64 s[0:1], s[16:17]
	s_cbranch_execz .LBB0_206
	v_lshlrev_b32_e32 v58, 16, v72
	v_and_b32_e32 v59, 0xffff0000, v72
	v_lshlrev_b32_e32 v72, 16, v73
	v_and_b32_e32 v73, 0xffff0000, v73
	v_pk_fma_f32 v[92:93], v[42:43], v[72:73], v[46:47]
	v_lshlrev_b32_e32 v72, 16, v74
	v_and_b32_e32 v73, 0xffff0000, v74
	v_pk_fma_f32 v[94:95], v[32:33], v[72:73], v[36:37]
	v_lshlrev_b32_e32 v72, 16, v75
	v_and_b32_e32 v73, 0xffff0000, v75
	v_pk_fma_f32 v[76:77], v[34:35], v[72:73], v[38:39]
	v_pk_fma_f32 v[58:59], v[40:41], v[58:59], v[44:45]
	v_mov_b32_e32 v96, v76
	v_mov_b32_e32 v97, v77

.LBB0_214:
	s_or_b64 exec, exec, s[0:1]
	v_cmp_gt_i32_e32 vcc, s12, v86
	v_add_u32_e32 v58, 1, v86
	v_mov_b64_e32 v[120:121], v[38:39]
	v_cndmask_b32_e32 v57, v83, v123, vcc
	v_add_u32_e32 v59, -1, v57
	v_and_b32_e32 v59, v59, v58
	v_or_b32_e32 v69, 2, v57
	v_cmp_lt_u32_e32 vcc, 1, v59
	v_cmp_lt_u32_e64 s[0:1], v59, v69
	s_and_b64 s[16:17], vcc, s[0:1]
	v_mov_b32_e32 v114, v44
	v_mov_b32_e32 v115, v45
	v_mov_b32_e32 v112, v46
	v_mov_b32_e32 v113, v47
	v_mov_b32_e32 v116, v36
	v_mov_b32_e32 v117, v37
	v_mov_b32_e32 v118, v38
	v_mov_b32_e32 v119, v39
	s_and_saveexec_b64 s[0:1], s[16:17]
	v_pk_fma_f32 v[120:121], v[34:35], v[104:105], v[38:39]
	v_pk_fma_f32 v[114:115], v[40:41], v[110:111], v[44:45]
	v_pk_fma_f32 v[112:113], v[42:43], v[108:109], v[46:47]
	v_pk_fma_f32 v[116:117], v[32:33], v[106:107], v[36:37]
	v_mov_b32_e32 v118, v120
	v_mov_b32_e32 v119, v121
	s_or_b64 exec, exec, s[0:1]
	v_add_u32_e32 v69, -1, v59
	v_cmp_lt_u32_e32 vcc, v69, v57
	s_and_saveexec_b64 s[0:1], vcc
	v_pk_fma_f32 v[114:115], v[0:1], v[76:77], v[114:115]
	v_pk_fma_f32 v[112:113], v[2:3], v[78:79], v[112:113]
	v_pk_fma_f32 v[116:117], v[4:5], v[100:101], v[116:117]
	v_pk_fma_f32 v[118:119], v[6:7], v[102:103], v[120:121]
	s_or_b64 exec, exec, s[0:1]
	v_and_b32_e32 v75, 0xffff0000, v52
	v_and_b32_e32 v73, 0xffff0000, v53
	v_and_b32_e32 v71, 0xffff0000, v54
	v_and_b32_e32 v69, 0xffff0000, v55
	v_add_u32_e32 v104, 1, v59
	v_pk_fma_f32 v[114:115], v[8:9], v[74:75], v[114:115]
	v_pk_fma_f32 v[112:113], v[10:11], v[72:73], v[112:113]
	v_pk_fma_f32 v[52:53], v[16:17], v[70:71], v[116:117]
	v_pk_fma_f32 v[54:55], v[18:19], v[68:69], v[118:119]
	v_cmp_lt_u32_e32 vcc, v104, v57
	s_and_saveexec_b64 s[0:1], vcc
	v_pk_fma_f32 v[114:115], v[12:13], v[98:99], v[114:115]
	v_pk_fma_f32 v[112:113], v[14:15], v[96:97], v[112:113]
	v_pk_fma_f32 v[52:53], v[20:21], v[92:93], v[52:53]
	v_pk_fma_f32 v[54:55], v[22:23], v[94:95], v[54:55]
	s_or_b64 exec, exec, s[0:1]
	v_add_u32_e32 v59, 2, v59
	v_cmp_lt_u32_e32 vcc, v59, v57
	s_waitcnt vmcnt(1)
	v_lshlrev_b32_e32 v110, 16, v64
	v_and_b32_e32 v111, 0xffff0000, v64
	v_lshlrev_b32_e32 v108, 16, v65
	v_and_b32_e32 v109, 0xffff0000, v65
	v_lshlrev_b32_e32 v106, 16, v66
	v_and_b32_e32 v107, 0xffff0000, v66
	v_lshlrev_b32_e32 v104, 16, v67
	v_and_b32_e32 v105, 0xffff0000, v67
	s_and_saveexec_b64 s[0:1], vcc
	v_pk_fma_f32 v[114:115], v[24:25], v[110:111], v[114:115]
	v_pk_fma_f32 v[112:113], v[26:27], v[108:109], v[112:113]
	v_pk_fma_f32 v[52:53], v[28:29], v[106:107], v[52:53]
	v_pk_fma_f32 v[54:55], v[30:31], v[104:105], v[54:55]
	s_or_b64 exec, exec, s[0:1]
	v_mul_f32_e32 v57, 0xbfb8aa3b, v114
	v_exp_f32_e32 v57, v57
	v_mul_f32_e32 v59, 0xbfb8aa3b, v115
	v_exp_f32_e32 v59, v59
	v_add_f32_e32 v57, 1.0, v57
	v_rcp_f32_e32 v116, v57
	v_add_f32_e32 v59, 1.0, v59
	v_mul_f32_e32 v57, 0xbfb8aa3b, v112
	v_rcp_f32_e32 v117, v59
	v_exp_f32_e32 v57, v57
	v_mul_f32_e32 v59, 0xbfb8aa3b, v113
	v_exp_f32_e32 v59, v59
	v_pk_mul_f32 v[114:115], v[114:115], v[116:117]
	v_add_f32_e32 v57, 1.0, v57
	v_rcp_f32_e32 v116, v57
	v_add_f32_e32 v57, 1.0, v59
	v_rcp_f32_e32 v117, v57
	v_mul_f32_e32 v57, 0xbfb8aa3b, v52
	v_exp_f32_e32 v57, v57
	v_mul_f32_e32 v59, 0xbfb8aa3b, v53
	v_exp_f32_e32 v59, v59
	v_pk_mul_f32 v[112:113], v[112:113], v[116:117]
	v_add_f32_e32 v57, 1.0, v57
	v_rcp_f32_e32 v116, v57
	v_add_f32_e32 v57, 1.0, v59
	v_mul_f32_e32 v59, 0xbfb8aa3b, v54
	v_cvt_pk_bf16_f32 v114, v114, v115
	v_exp_f32_e32 v59, v59
	v_mul_f32_e32 v115, 0xbfb8aa3b, v55
	v_exp_f32_e32 v115, v115
	v_rcp_f32_e32 v117, v57
	v_add_f32_e32 v57, 1.0, v59
	v_rcp_f32_e32 v118, v57
	v_add_f32_e32 v57, 1.0, v115
	v_rcp_f32_e32 v119, v57
	v_pk_mul_f32 v[52:53], v[52:53], v[116:117]
	v_ashrrev_i32_e32 v59, 31, v58
	v_cvt_pk_bf16_f32 v116, v52, v53
	v_pk_mul_f32 v[52:53], v[54:55], v[118:119]
	v_cvt_pk_bf16_f32 v115, v112, v113
	v_cvt_pk_bf16_f32 v117, v52, v53
	v_lshlrev_b64 v[52:53], 9, v[58:59]
	v_lshl_add_u64 v[52:53], v[80:81], 0, v[52:53]
	global_store_dwordx4 v[52:53], v[114:117], off
	v_add_u32_e32 v52, 5, v86
	v_mov_b32_e32 v57, v56
	v_cmp_gt_u32_e32 vcc, s10, v52
	v_mov_b32_e32 v58, v56
	v_mov_b32_e32 v59, v56
	v_mov_b64_e32 v[52:53], v[56:57]
	v_mov_b64_e32 v[54:55], v[58:59]
	s_and_saveexec_b64 s[0:1], vcc
	s_cbranch_execz .LBB0_224
	v_add_u32_e32 v52, 0xa00, v124
	v_mov_b32_e32 v53, v56
	v_lshl_add_u64 v[52:53], v[84:85], 0, v[52:53]
	global_load_dwordx4 v[52:55], v[52:53], off
